# P1 GEMM on 216 WGs (9 rounds), 40 converter WGs run 64000 deferred conversion items concurrently; PLE GEMM in P3b
# baseline (speedup 1.0000x reference)
.LBB0_9:
	s_cmp_lg_u32 s101, 0
	s_cbranch_scc1 .Lcv_go
	s_cmp_lt_i32 s80, 0xb080
	s_cbranch_scc1 .Lcv_go
	s_cmp_lt_i32 s80, 0x1aa80
	s_cbranch_scc1 .LBB0_8

.LBB0_109:
	s_or_b64 exec, exec, s[0:1]
	v_writelane_b32 v250, s86, 10
	s_waitcnt lgkmcnt(0)
	s_barrier
	v_writelane_b32 v250, s87, 11
	v_mbcnt_lo_u32_b32 v0, -1, 0
	v_mbcnt_hi_u32_b32 v0, -1, v0
	s_cmpk_eq_i32 s88, 0x100
	s_cselect_b32 s99, 0xd8, s88
	s_min_i32 s98, s99, 0x774
	s_cmp_lt_i32 s2, s98
	s_load_dwordx4 s[28:31], s[86:87], 0xb8
	s_cselect_b64 s[0:1], -1, 0
	v_mbcnt_lo_u32_b32 v8, -1, 0
	v_mbcnt_hi_u32_b32 v8, -1, v8
	s_and_b64 vcc, exec, s[0:1]
	s_cbranch_vccz .LBB0_111
	s_ashr_i32 s4, s2, 31
	s_lshr_b32 s4, s4, 29
	s_add_i32 s4, s2, s4
	s_and_b32 s5, s4, -8
	s_sub_i32 s5, s2, s5
	s_mul_i32 s7, s5, 0xee
	s_add_i32 s7, s7, 4
	s_ashr_i32 s4, s4, 3
	s_mul_i32 s6, s5, 0xef
	s_cmp_lt_i32 s5, 4
	s_cselect_b32 s5, s6, s7
	s_add_i32 s5, s5, s4
	s_mul_hi_i32 s4, s5, 0x4d4873ed
	s_lshr_b32 s6, s4, 31
	s_ashr_i32 s4, s4, 7
	s_add_i32 s4, s4, s6
	s_lshl_b32 s6, s4, 3
	s_sub_i32 s7, 36, s6
	s_mulk_i32 s4, 0x1a8
	s_min_u32 s7, s7, 8
	s_sub_i32 s8, s5, s4
	s_sext_i32_i16 s4, s8
	v_cvt_f32_ubyte0_e32 v1, s7
	v_cvt_f32_i32_e32 v0, s4
	v_rcp_iflag_f32_e32 v2, v1
	s_ashr_i32 s4, s4, 30
	s_or_b32 s9, s4, 1
	v_mul_f32_e32 v2, v0, v2
	v_trunc_f32_e32 v2, v2
	v_fma_f32 v0, -v2, v1, v0
	v_cvt_i32_f32_e32 v2, v2
	v_cmp_ge_f32_e64 s[4:5], |v0|, v1
	s_and_b64 s[4:5], s[4:5], exec
	s_cselect_b32 s4, s9, 0
	v_readfirstlane_b32 s5, v2
	s_add_i32 s4, s5, s4
	s_sext_i32_i16 s14, s4
	s_mul_i32 s4, s4, s7
	s_sub_i32 s4, s8, s4
	s_sext_i32_i16 s4, s4
	s_add_i32 s20, s6, s4

.LBB0_117:
	s_add_i32 s74, s74, 1
	s_mul_i32 s12, s74, s99
	s_mov_b32 s13, 0
	s_add_u32 s22, s12, s2
	s_addc_u32 s23, s13, s33
	v_cmp_gt_i64_e32 vcc, s[22:23], v[152:153]
	v_cmp_lt_i64_e64 s[12:13], s[22:23], v[150:151]
	s_cbranch_vccnz .LBB0_123
	s_ashr_i32 s15, s22, 31
	s_lshr_b32 s15, s15, 29
	s_add_i32 s15, s22, s15
	s_and_b32 s21, s15, -8
	s_sub_i32 s21, s22, s21
	s_cmp_gt_i32 s21, 3
	s_mov_b64 s[22:23], -1
	s_cbranch_scc0 .LBB0_120
	s_mul_i32 s22, s21, 0xee
	s_add_i32 s24, s22, 4
	s_mov_b64 s[22:23], 0

.LBB0_399:
	s_cmpk_eq_i32 s88, 0x100
	s_cselect_b64 s[0:1], -1, 0
	s_cmpk_lg_i32 s88, 0x100
	v_writelane_b32 v250, s0, 23
	s_cselect_b64 s[22:23], -1, 0
	s_cmp_lt_i32 s2, s99
	v_writelane_b32 v250, s1, 24
	s_cselect_b64 s[0:1], -1, 0
	s_or_b64 s[0:1], s[0:1], s[22:23]
	s_and_b64 vcc, exec, s[0:1]
	s_cbranch_vccnz .LBB0_416
	v_writelane_b32 v248, s0, 0
	v_writelane_b32 v248, s1, 1
	v_writelane_b32 v248, s2, 2
	v_writelane_b32 v248, s3, 3
	v_writelane_b32 v248, s4, 4
	v_writelane_b32 v248, s5, 5
	v_writelane_b32 v248, s6, 6
	v_writelane_b32 v248, s7, 7
	v_writelane_b32 v248, s8, 8
	v_writelane_b32 v248, s9, 9
	v_writelane_b32 v248, s10, 10
	v_writelane_b32 v248, s11, 11
	v_writelane_b32 v248, s12, 12
	v_writelane_b32 v248, s13, 13
	v_writelane_b32 v248, s14, 14
	v_writelane_b32 v248, s15, 15
	v_writelane_b32 v248, s16, 16
	v_writelane_b32 v248, s17, 17
	v_writelane_b32 v248, s18, 18
	v_writelane_b32 v248, s19, 19
	v_writelane_b32 v248, s20, 20
	v_writelane_b32 v248, s21, 21
	v_writelane_b32 v248, s22, 22
	v_writelane_b32 v248, s23, 23
	v_writelane_b32 v248, s24, 24
	v_writelane_b32 v248, s25, 25
	v_writelane_b32 v248, s26, 26
	v_writelane_b32 v248, s27, 27
	v_writelane_b32 v248, s28, 28
	v_writelane_b32 v248, s29, 29
	v_writelane_b32 v248, s30, 30
	v_writelane_b32 v248, s31, 31
	v_writelane_b32 v248, s32, 32
	v_writelane_b32 v248, s33, 33
	v_writelane_b32 v248, s34, 34
	v_writelane_b32 v248, s35, 35
	v_writelane_b32 v248, s36, 36
	v_writelane_b32 v248, s37, 37
	v_writelane_b32 v248, s38, 38
	v_writelane_b32 v248, s39, 39
	v_writelane_b32 v248, s40, 40
	v_writelane_b32 v248, s41, 41
	v_writelane_b32 v248, s42, 42
	v_writelane_b32 v248, s43, 43
	v_writelane_b32 v248, s44, 44
	v_writelane_b32 v248, s45, 45
	v_writelane_b32 v248, s46, 46
	v_writelane_b32 v248, s47, 47
	v_writelane_b32 v248, s48, 48
	v_writelane_b32 v248, s49, 49
	v_writelane_b32 v248, s50, 50
	v_writelane_b32 v248, s51, 51
	v_writelane_b32 v248, s52, 52
	v_writelane_b32 v248, s53, 53
	v_writelane_b32 v248, s54, 54
	v_writelane_b32 v248, s55, 55
	v_writelane_b32 v248, s56, 56
	v_writelane_b32 v248, s57, 57
	v_writelane_b32 v248, s58, 58
	v_writelane_b32 v248, s59, 59
	v_writelane_b32 v248, s60, 60
	v_writelane_b32 v248, s61, 61
	v_writelane_b32 v248, s62, 62
	v_writelane_b32 v248, s63, 63
	v_writelane_b32 v249, s64, 0
	v_writelane_b32 v249, s65, 1
	v_writelane_b32 v249, s66, 2
	v_writelane_b32 v249, s67, 3
	v_writelane_b32 v249, s68, 4
	v_writelane_b32 v249, s69, 5
	v_writelane_b32 v249, s70, 6
	v_writelane_b32 v249, s71, 7
	v_writelane_b32 v249, s72, 8
	v_writelane_b32 v249, s73, 9
	v_writelane_b32 v249, s74, 10
	v_writelane_b32 v249, s75, 11
	v_writelane_b32 v249, s76, 12
	v_writelane_b32 v249, s77, 13
	v_writelane_b32 v249, s78, 14
	v_writelane_b32 v249, s79, 15
	v_writelane_b32 v249, s80, 16
	v_writelane_b32 v249, s81, 17
	v_writelane_b32 v249, s82, 18
	v_writelane_b32 v249, s83, 19
	v_writelane_b32 v249, s84, 20
	v_writelane_b32 v249, s85, 21
	v_writelane_b32 v249, s86, 22
	v_writelane_b32 v249, s87, 23
	v_writelane_b32 v249, s88, 24
	v_writelane_b32 v249, s89, 25
	v_writelane_b32 v249, s90, 26
	v_writelane_b32 v249, s91, 27
	v_writelane_b32 v249, s92, 28
	v_writelane_b32 v249, s93, 29
	v_writelane_b32 v249, s94, 30
	v_writelane_b32 v249, s95, 31
	v_writelane_b32 v249, s96, 32
	v_writelane_b32 v249, s97, 33
	v_readlane_b32 s1, v250, 9
	v_readlane_b32 s86, v250, 10
	v_readlane_b32 s87, v250, 11
	s_sub_i32 s0, s2, s99
	s_lshl_b32 s0, s0, 3
	s_nop 1
	s_add_i32 s12, s0, s1
	s_add_i32 s12, s12, 0xb080
	s_movk_i32 s14, 0x140
	s_mov_b32 s100, 0x1aa80
	s_mov_b32 s101, 1
	s_branch .Lcv_entry
